# weight conversion: job lookup by one vector compare against a tile0 table in a VGPR instead of a scalar-load loop per tile; all four source loads of a tile in flight
# baseline (speedup 1.0000x reference)
; __device__ __forceinline__ void phase_cvt(const Params& p, int l, char* smem) {
;   const int total = p.job_tiles[l];
;   for (int t = blockIdx.x; t < total; t += gridDim.x) {
;     int ji = 0;
; #pragma unroll 1
;     for (int q = 1; q < 15; ++q) if (t >= p.jobs[l * 15 + q].tile0) ji = q;
;     const CvtJob& j = p.jobs[l * 15 + ji];
.Lcvt_all:
	s_cmp_ge_i32 s101, s22
	s_cbranch_scc1 .Lcvt_exit
	s_and_b64 s[34:35], s[28:29], exec
	s_cselect_b32 s23, 15, 0
	s_mov_b32 s44, s23
	s_mov_b32 s45, s101
	s_mul_i32 s34, s23, 48
	s_addk_i32 s34, 0x134
	v_and_b32_e32 v247, 63, v172
	v_min_u32_e32 v247, 14, v247
	v_mov_b32_e32 v248, s34
	v_mad_u32_u24 v247, v247, 48, v248
	global_load_dword v248, v247, s[0:1]
	s_waitcnt vmcnt(0)
	s_branch .LBB0_36

; __device__ __forceinline__ int otid() { int t = threadIdx.x; asm volatile("" : "+v"(t)); return t; }
; __device__ __forceinline__ void cvt_tile(const CvtJob& j, int t, char* smem) {
;   float* ts = (float*)smem;
;   const int tid = otid();
;   const int tk = t % j.ntk, tn = t / j.ntk, k0 = tk * 64, n0 = tn * 64;
;   {
;     const int n4 = (tid & 15) * 4, n = n0 + n4, kr = tid >> 4;
;     float4 v[4];
; #pragma unroll
;     for (int i = 0; i < 4; ++i) {
;       const int k = kr + 16 * i;
;       v[i] = (n < j.nsrc) ? *(const float4*)(j.src + (size_t)(k0 + k) * j.ld_src + n) : float4{0.f, 0.f, 0.f, 0.f};
; __device__ __forceinline__ void phase_cvt(const Params& p, int l, char* smem) {
;     ...
;   for (int t = blockIdx.x; t < total; t += gridDim.x) {
;     int ji = 0;
; #pragma unroll 1
;     for (int q = 1; q < 15; ++q) if (t >= p.jobs[l * 15 + q].tile0) ji = q;
;     const CvtJob& j = p.jobs[l * 15 + ji];
;     cvt_tile(j, t - j.tile0, smem);
.LBB0_36:
	v_cmp_ge_i32_e32 vcc, s45, v248
	s_and_b32 s34, vcc_lo, 0x7fff
	s_bcnt1_i32_b32 s34, s34
	s_add_i32 s34, s34, -1
	s_add_i32 s34, s34, s23
	s_mul_hi_u32 s35, s34, 48
	s_mul_i32 s34, s34, 48
	s_add_u32 s36, s0, s34
	s_addc_u32 s37, s1, s35
	s_load_dwordx2 s[34:35], s[36:37], 0x130
	s_load_dwordx2 s[42:43], s[36:37], 0x108
	s_load_dwordx2 s[40:41], s[36:37], 0x120
	v_mov_b32_e32 v20, v172
	s_waitcnt vmcnt(2)
	v_mov_b32_e32 v6, 0
	s_waitcnt lgkmcnt(0)
	s_abs_i32 s46, s34
	v_cvt_f32_u32_e32 v0, s46
	s_sub_i32 s49, 0, s46
	s_sub_i32 s35, s45, s35
	s_abs_i32 s48, s35
	v_rcp_iflag_f32_e32 v0, v0
	s_xor_b32 s47, s35, s34
	s_ashr_i32 s47, s47, 31
	v_ashrrev_i32_e32 v21, 4, v20
	v_mul_f32_e32 v0, 0x4f7ffffe, v0
	v_cvt_u32_f32_e32 v0, v0
	v_mov_b32_e32 v7, 0
	v_mov_b32_e32 v8, 0
	v_mov_b32_e32 v9, 0
	v_readfirstlane_b32 s50, v0
	s_mul_i32 s49, s49, s50
	s_mul_hi_u32 s49, s50, s49
	s_add_i32 s50, s50, s49
	s_mul_hi_u32 s49, s48, s50
	s_mul_i32 s50, s49, s46
	s_sub_i32 s48, s48, s50
	s_add_i32 s51, s49, 1
	s_sub_i32 s50, s48, s46
	s_cmp_ge_u32 s48, s46
	s_cselect_b32 s49, s51, s49
	s_cselect_b32 s48, s50, s48
	s_add_i32 s50, s49, 1
	s_cmp_ge_u32 s48, s46
	s_cselect_b32 s46, s50, s49
	s_xor_b32 s46, s46, s47
	s_sub_i32 s46, s46, s47
	v_lshlrev_b32_e32 v0, 2, v20
	s_mul_i32 s34, s46, s34
	s_lshl_b32 s46, s46, 6
	v_and_b32_e32 v0, 60, v0
	s_sub_i32 s34, s35, s34
	v_or_b32_e32 v2, s46, v0
	s_lshl_b32 s34, s34, 6
	v_ashrrev_i32_e32 v3, 31, v2
	v_cmp_gt_i32_e32 vcc, s40, v2
	v_add_u32_e32 v22, s34, v21
	v_lshl_add_u64 v[18:19], v[2:3], 2, s[42:43]
	v_mov_b32_e32 v2, 0
	s_and_saveexec_b64 s[42:43], vcc
	s_cbranch_execz .LBB0_40
	v_mad_i64_i32 v[4:5], s[48:49], s41, v22, 0
	v_lshl_add_u64 v[4:5], v[4:5], 2, v[18:19]
	global_load_dwordx4 v[6:9], v[4:5], off

; __device__ __forceinline__ void cvt_tile(const CvtJob& j, int t, char* smem) {
;     ...
;   {
;     const int n4 = (tid & 15) * 4, n = n0 + n4, kr = tid >> 4;
;     float4 v[4];
; #pragma unroll
;     for (int i = 0; i < 4; ++i) {
;       const int k = kr + 16 * i;
;       v[i] = (n < j.nsrc) ? *(const float4*)(j.src + (size_t)(k0 + k) * j.ld_src + n) : float4{0.f, 0.f, 0.f, 0.f};
;     }
.LBB0_42:
	s_or_b64 exec, exec, s[42:43]
	v_mov_b32_e32 v10, 0
	v_mov_b32_e32 v14, 0
	v_mov_b32_e32 v15, 0
	v_mov_b32_e32 v16, 0
	v_mov_b32_e32 v17, 0
	s_and_saveexec_b64 s[42:43], vcc
	s_cbranch_execz .LBB0_44
	v_add_u32_e32 v11, 32, v22
	v_mad_i64_i32 v[12:13], s[48:49], s41, v11, 0
	v_lshl_add_u64 v[12:13], v[12:13], 2, v[18:19]
	global_load_dwordx4 v[14:17], v[12:13], off
